# GEMM unit loops: accumulators zeroed with v_mov_b64 (half the instructions)
# baseline (speedup 1.0000x reference)
.LBB0_105:
	s_ashr_i32 s71, s70, 31
	s_lshl_b64 s[6:7], s[70:71], 19
	v_readlane_b32 s28, v254, 41
	v_readlane_b32 s29, v254, 42
	s_add_u32 s72, s28, s6
	s_addc_u32 s73, s29, s7
	s_and_b64 s[6:7], s[40:41], exec
	s_cselect_b32 s6, s73, s5
	s_cselect_b32 s7, s72, s4
	s_ashr_i32 s69, s68, 31
	s_lshl_b64 s[28:29], s[68:69], 19
	s_add_u32 s74, s9, s28
	s_addc_u32 s75, s10, s29
	s_and_b64 s[28:29], s[40:41], exec
	s_cselect_b32 s27, s75, s1
	s_cselect_b32 s28, s74, s0
	s_add_u32 s42, s4, 0x40080
	s_addc_u32 s43, s5, 0
	s_add_u32 s29, s0, 0x100
	v_mov_b32_e32 v14, 0
	s_addc_u32 s34, s1, 0
	s_mov_b32 s35, -2
	v_mov_b32_e32 v15, 0
	v_mov_b64_e32 v[16:17], 0
	v_mov_b64_e32 v[82:83], 0
	v_mov_b64_e32 v[84:85], 0
	v_mov_b64_e32 v[2:3], 0
	v_mov_b64_e32 v[4:5], 0
	v_mov_b64_e32 v[66:67], 0
	v_mov_b64_e32 v[68:69], 0
	v_mov_b64_e32 v[6:7], 0
	v_mov_b64_e32 v[8:9], 0
	v_mov_b64_e32 v[70:71], 0
	v_mov_b64_e32 v[72:73], 0
	v_mov_b64_e32 v[26:27], 0
	v_mov_b64_e32 v[28:29], 0
	v_mov_b64_e32 v[90:91], 0
	v_mov_b64_e32 v[92:93], 0
	v_mov_b64_e32 v[22:23], 0
	v_mov_b64_e32 v[24:25], 0
	v_mov_b64_e32 v[86:87], 0
	v_mov_b64_e32 v[88:89], 0
	v_mov_b64_e32 v[10:11], 0
	v_mov_b64_e32 v[12:13], 0
	v_mov_b64_e32 v[74:75], 0
	v_mov_b64_e32 v[76:77], 0
	v_mov_b64_e32 v[18:19], 0
	v_mov_b64_e32 v[20:21], 0
	v_mov_b64_e32 v[78:79], 0
	v_mov_b64_e32 v[80:81], 0
	v_mov_b64_e32 v[30:31], 0
	v_mov_b64_e32 v[32:33], 0
	v_mov_b64_e32 v[94:95], 0
	v_mov_b64_e32 v[96:97], 0
	v_mov_b64_e32 v[50:51], 0
	v_mov_b64_e32 v[52:53], 0
	s_waitcnt vmcnt(0)
	v_mov_b64_e32 v[114:115], 0
	v_mov_b64_e32 v[116:117], 0
	v_mov_b64_e32 v[34:35], 0
	v_mov_b64_e32 v[36:37], 0
	v_mov_b64_e32 v[98:99], 0
	v_mov_b64_e32 v[100:101], 0
	v_mov_b64_e32 v[38:39], 0
	v_mov_b64_e32 v[40:41], 0
	v_mov_b64_e32 v[102:103], 0
	v_mov_b64_e32 v[104:105], 0
	v_mov_b64_e32 v[58:59], 0
	v_mov_b64_e32 v[60:61], 0
	v_mov_b64_e32 v[122:123], 0
	v_mov_b64_e32 v[124:125], 0
	v_mov_b64_e32 v[54:55], 0
	v_mov_b64_e32 v[56:57], 0
	v_mov_b64_e32 v[118:119], 0
	v_mov_b64_e32 v[120:121], 0
	v_mov_b64_e32 v[42:43], 0
	v_mov_b64_e32 v[44:45], 0
	v_mov_b64_e32 v[106:107], 0
	v_mov_b64_e32 v[108:109], 0
	v_mov_b64_e32 v[46:47], 0
	v_mov_b64_e32 v[48:49], 0
	v_mov_b64_e32 v[110:111], 0
	v_mov_b64_e32 v[112:113], 0
	v_mov_b64_e32 v[62:63], 0
	v_mov_b64_e32 v[64:65], 0
	v_mov_b64_e32 v[126:127], 0
	v_mov_b64_e32 v[128:129], 0
	s_mov_b64 s[80:81], 0x80

.LBB0_161:
	s_ashr_i32 s49, s48, 31
	s_lshl_b64 s[4:5], s[48:49], 19
	s_add_u32 s56, s8, s4
	s_addc_u32 s57, s9, s5
	s_and_b64 s[4:5], s[42:43], exec
	s_cselect_b32 s4, s57, s3
	s_cselect_b32 s5, s56, s2
	s_ashr_i32 s45, s44, 31
	s_lshl_b64 s[22:23], s[44:45], 19
	s_add_u32 s60, s10, s22
	s_addc_u32 s61, s11, s23
	s_and_b64 s[22:23], s[42:43], exec
	s_cselect_b32 s22, s61, s1
	s_cselect_b32 s23, s60, s0
	s_add_u32 s66, s2, 0x40080
	s_addc_u32 s67, s3, 0
	s_add_u32 s24, s0, 0x100
	v_mov_b32_e32 v2, 0
	s_addc_u32 s25, s1, 0
	s_mov_b32 s26, -2
	v_mov_b32_e32 v3, 0
	v_mov_b64_e32 v[4:5], 0
	v_mov_b64_e32 v[6:7], 0
	v_mov_b64_e32 v[8:9], 0
	v_mov_b64_e32 v[18:19], 0
	v_mov_b64_e32 v[20:21], 0
	v_mov_b64_e32 v[22:23], 0
	v_mov_b64_e32 v[24:25], 0
	v_mov_b64_e32 v[34:35], 0
	v_mov_b64_e32 v[36:37], 0
	v_mov_b64_e32 v[38:39], 0
	v_mov_b64_e32 v[40:41], 0
	v_mov_b64_e32 v[50:51], 0
	v_mov_b64_e32 v[52:53], 0
	v_mov_b64_e32 v[54:55], 0
	v_mov_b64_e32 v[56:57], 0
	v_mov_b64_e32 v[10:11], 0
	v_mov_b64_e32 v[12:13], 0
	v_mov_b64_e32 v[14:15], 0
	v_mov_b64_e32 v[16:17], 0
	v_mov_b64_e32 v[26:27], 0
	v_mov_b64_e32 v[28:29], 0
	v_mov_b64_e32 v[30:31], 0
	v_mov_b64_e32 v[32:33], 0
	v_mov_b64_e32 v[42:43], 0
	v_mov_b64_e32 v[44:45], 0
	v_mov_b64_e32 v[46:47], 0
	v_mov_b64_e32 v[48:49], 0
	v_mov_b64_e32 v[58:59], 0
	v_mov_b64_e32 v[60:61], 0
	v_mov_b64_e32 v[62:63], 0
	v_mov_b64_e32 v[64:65], 0
	v_mov_b64_e32 v[66:67], 0
	v_mov_b64_e32 v[68:69], 0
	v_mov_b64_e32 v[70:71], 0
	v_mov_b64_e32 v[72:73], 0
	v_mov_b64_e32 v[82:83], 0
	v_mov_b64_e32 v[84:85], 0
	v_mov_b64_e32 v[86:87], 0
	v_mov_b64_e32 v[88:89], 0
	v_mov_b64_e32 v[98:99], 0
	v_mov_b64_e32 v[100:101], 0
	v_mov_b64_e32 v[102:103], 0
	v_mov_b64_e32 v[104:105], 0
	v_mov_b64_e32 v[138:139], 0
	v_mov_b64_e32 v[140:141], 0
	v_mov_b64_e32 v[142:143], 0
	v_mov_b64_e32 v[144:145], 0
	v_mov_b64_e32 v[74:75], 0
	v_mov_b64_e32 v[76:77], 0
	v_mov_b64_e32 v[78:79], 0
	v_mov_b64_e32 v[80:81], 0
	v_mov_b64_e32 v[90:91], 0
	v_mov_b64_e32 v[92:93], 0
	v_mov_b64_e32 v[94:95], 0
	v_mov_b64_e32 v[96:97], 0
	v_mov_b64_e32 v[106:107], 0
	v_mov_b64_e32 v[108:109], 0
	v_mov_b64_e32 v[110:111], 0
	v_mov_b64_e32 v[112:113], 0
	v_mov_b64_e32 v[146:147], 0
	v_mov_b64_e32 v[148:149], 0
	v_mov_b64_e32 v[150:151], 0
	v_mov_b64_e32 v[152:153], 0
	s_mov_b64 s[78:79], 0x80

.LBB0_190:
	s_add_u32 s18, s78, 0x17d00000
	s_addc_u32 s19, s79, 0
	v_lshrrev_b32_e32 v17, 1, v11
	s_add_u32 s36, s78, 0x10d00000
	v_and_b32_e32 v17, 24, v17
	s_addc_u32 s37, s79, 0
	v_and_b32_e32 v16, 15, v11
	v_lshlrev_b32_e32 v18, 1, v17
	v_lshlrev_b32_e32 v11, 2, v11
	s_lshl_b32 s1, s1, 5
	v_lshl_or_b32 v202, s2, 6, v16
	v_lshl_or_b32 v16, v16, 6, v18
	s_lshl_b32 s2, s2, 13
	v_and_b32_e32 v11, 32, v11
	s_and_b32 s1, s1, 0x60
	v_bitop3_b32 v18, v16, s2, v11 bitop3:0xde
	s_lshl_b32 s2, s1, 7
	v_bitop3_b32 v203, v16, s2, v11 bitop3:0xde
	s_mov_b64 s[2:3], 0x80
	s_add_i32 m0, s14, 0x18000
	v_lshl_add_u64 v[8:9], v[8:9], 0, s[2:3]
	s_waitcnt vmcnt(2)
	s_barrier
	global_load_lds_dwordx4 v[8:9], off
	v_lshl_add_u64 v[6:7], v[6:7], 0, s[2:3]
	s_add_i32 m0, s14, 0x1a000
	s_add_i32 s20, s14, 0x8000
	global_load_lds_dwordx4 v[6:7], off
	v_lshl_add_u64 v[2:3], v[2:3], 0, s[2:3]
	s_mov_b32 m0, s20
	s_add_i32 s21, s14, 0xa000
	global_load_lds_dwordx4 v[2:3], off
	v_lshl_add_u64 v[2:3], v[4:5], 0, s[2:3]
	s_add_u32 s2, s4, 0x20080
	s_mov_b32 m0, s21
	s_addc_u32 s3, s5, 0
	global_load_lds_dwordx4 v[2:3], off
	s_add_i32 m0, s14, 0x1c000
	v_lshl_add_u64 v[2:3], s[2:3], 0, v[134:135]
	global_load_lds_dwordx4 v[2:3], off
	v_lshl_add_u64 v[2:3], s[2:3], 0, v[130:131]
	s_add_i32 m0, s14, 0x1e000
	s_cmpk_lt_u32 s0, 0x100
	global_load_lds_dwordx4 v[2:3], off
	v_lshlrev_b32_e32 v2, 13, v14
	v_and_b32_e32 v2, 0xffffc000, v2
	v_lshl_add_u32 v2, v13, 10, v2
	v_and_b32_e32 v3, 1, v14
	v_lshl_or_b32 v2, v3, 6, v2
	v_lshl_add_u32 v138, v15, 1, v2
	v_lshlrev_b32_e32 v2, 13, v0
	v_and_b32_e32 v2, 0xffffc000, v2
	s_waitcnt vmcnt(6)
	v_lshl_add_u32 v2, v10, 10, v2
	v_and_b32_e32 v0, 1, v0
	v_lshl_or_b32 v0, v0, 6, v2
	v_mov_b32_e32 v2, 0
	s_cselect_b64 s[38:39], -1, 0
	v_or_b32_e32 v204, s1, v17
	v_mov_b32_e32 v139, v1
	v_lshl_add_u32 v140, v12, 1, v0
	v_mov_b32_e32 v141, v1
	s_mov_b32 s22, 0
	v_add_u32_e32 v205, 0, v18
	v_mov_b32_e32 v3, 0
	v_mov_b64_e32 v[4:5], 0
	v_mov_b64_e32 v[6:7], 0
	v_mov_b64_e32 v[8:9], 0
	v_mov_b64_e32 v[10:11], 0
	v_mov_b64_e32 v[12:13], 0
	v_mov_b64_e32 v[14:15], 0
	v_mov_b64_e32 v[16:17], 0
	v_mov_b64_e32 v[18:19], 0
	v_mov_b64_e32 v[20:21], 0
	v_mov_b64_e32 v[22:23], 0
	v_mov_b64_e32 v[24:25], 0
	v_mov_b64_e32 v[26:27], 0
	v_mov_b64_e32 v[28:29], 0
	v_mov_b64_e32 v[30:31], 0
	v_mov_b64_e32 v[32:33], 0
	v_mov_b64_e32 v[34:35], 0
	v_mov_b64_e32 v[36:37], 0
	v_mov_b64_e32 v[38:39], 0
	v_mov_b64_e32 v[40:41], 0
	v_mov_b64_e32 v[42:43], 0
	v_mov_b64_e32 v[44:45], 0
	v_mov_b64_e32 v[46:47], 0
	v_mov_b64_e32 v[48:49], 0
	v_mov_b64_e32 v[50:51], 0
	v_mov_b64_e32 v[52:53], 0
	v_mov_b64_e32 v[54:55], 0
	v_mov_b64_e32 v[56:57], 0
	v_mov_b64_e32 v[58:59], 0
	v_mov_b64_e32 v[60:61], 0
	v_mov_b64_e32 v[62:63], 0
	v_mov_b64_e32 v[64:65], 0
	v_mov_b64_e32 v[70:71], 0
	v_mov_b64_e32 v[72:73], 0
	v_mov_b64_e32 v[66:67], 0
	v_mov_b64_e32 v[68:69], 0
	v_mov_b64_e32 v[78:79], 0
	v_mov_b64_e32 v[80:81], 0
	v_mov_b64_e32 v[74:75], 0
	v_mov_b64_e32 v[76:77], 0
	v_mov_b64_e32 v[86:87], 0
	v_mov_b64_e32 v[88:89], 0
	v_mov_b64_e32 v[82:83], 0
	v_mov_b64_e32 v[84:85], 0
	v_mov_b64_e32 v[94:95], 0
	v_mov_b64_e32 v[96:97], 0
	v_mov_b64_e32 v[90:91], 0
	v_mov_b64_e32 v[92:93], 0
	v_mov_b64_e32 v[102:103], 0
	v_mov_b64_e32 v[104:105], 0
	v_mov_b64_e32 v[98:99], 0
	v_mov_b64_e32 v[100:101], 0
	v_mov_b64_e32 v[110:111], 0
	v_mov_b64_e32 v[112:113], 0
	v_mov_b64_e32 v[106:107], 0
	v_mov_b64_e32 v[108:109], 0
	s_waitcnt vmcnt(0)
	v_mov_b32_e32 v118, v2
	v_mov_b32_e32 v119, v2
	v_mov_b32_e32 v120, v2
	v_mov_b32_e32 v121, v2
	v_mov_b32_e32 v114, v2
	v_mov_b32_e32 v115, v2
	v_mov_b32_e32 v116, v2
	v_mov_b32_e32 v117, v2
	v_mov_b32_e32 v126, v2
	v_mov_b32_e32 v127, v2
	v_mov_b32_e32 v128, v2
	v_mov_b32_e32 v129, v2
	v_mov_b32_e32 v122, v2
	v_mov_b32_e32 v123, v2
	v_mov_b32_e32 v124, v2
	v_mov_b32_e32 v125, v2
	s_barrier
	s_branch .LBB0_193

.LBB0_298:
	s_cmp_lt_i32 s23, 8
	s_cbranch_scc1 .LBB0_300
	v_mov_b32_e32 v2, 0
	v_mov_b32_e32 v3, 0
	v_mov_b64_e32 v[4:5], 0
	v_mov_b64_e32 v[6:7], 0
	v_mov_b64_e32 v[8:9], 0
	v_mov_b64_e32 v[10:11], 0
	v_mov_b64_e32 v[12:13], 0
	v_mov_b64_e32 v[14:15], 0
	v_mov_b64_e32 v[16:17], 0
	v_mov_b64_e32 v[18:19], 0
	v_mov_b64_e32 v[20:21], 0
	v_mov_b64_e32 v[22:23], 0
	v_mov_b64_e32 v[24:25], 0
	v_mov_b64_e32 v[26:27], 0
	v_mov_b64_e32 v[28:29], 0
	v_mov_b64_e32 v[30:31], 0
	v_mov_b64_e32 v[32:33], 0
	v_mov_b64_e32 v[34:35], 0
	v_mov_b64_e32 v[36:37], 0
	v_mov_b64_e32 v[38:39], 0
	v_mov_b64_e32 v[40:41], 0
	v_mov_b64_e32 v[42:43], 0
	v_mov_b64_e32 v[44:45], 0
	v_mov_b64_e32 v[46:47], 0
	v_mov_b64_e32 v[48:49], 0
	v_mov_b64_e32 v[50:51], 0
	v_mov_b64_e32 v[52:53], 0
	v_mov_b64_e32 v[54:55], 0
	v_mov_b64_e32 v[56:57], 0
	v_mov_b64_e32 v[58:59], 0
	v_mov_b64_e32 v[60:61], 0
	v_mov_b64_e32 v[62:63], 0
	v_mov_b64_e32 v[64:65], 0
	v_mov_b64_e32 v[70:71], 0
	v_mov_b64_e32 v[72:73], 0
	v_mov_b64_e32 v[66:67], 0
	v_mov_b64_e32 v[68:69], 0
	v_mov_b64_e32 v[78:79], 0
	v_mov_b64_e32 v[80:81], 0
	v_mov_b64_e32 v[74:75], 0
	v_mov_b64_e32 v[76:77], 0
	v_mov_b64_e32 v[86:87], 0
	v_mov_b64_e32 v[88:89], 0
	v_mov_b64_e32 v[82:83], 0
	v_mov_b64_e32 v[84:85], 0
	v_mov_b64_e32 v[94:95], 0
	v_mov_b64_e32 v[96:97], 0
	v_mov_b64_e32 v[90:91], 0
	v_mov_b64_e32 v[92:93], 0
	v_mov_b64_e32 v[102:103], 0
	v_mov_b64_e32 v[104:105], 0
	v_mov_b64_e32 v[98:99], 0
	v_mov_b64_e32 v[100:101], 0
	v_mov_b64_e32 v[110:111], 0
	v_mov_b64_e32 v[112:113], 0
	v_mov_b64_e32 v[106:107], 0
	v_mov_b64_e32 v[108:109], 0
	v_mov_b64_e32 v[118:119], 0
	v_mov_b64_e32 v[120:121], 0
	v_mov_b64_e32 v[114:115], 0
	v_mov_b64_e32 v[116:117], 0
	v_mov_b64_e32 v[126:127], 0
	v_mov_b64_e32 v[128:129], 0
	v_mov_b64_e32 v[122:123], 0
	v_mov_b64_e32 v[124:125], 0

.LBB0_661:
	s_add_u32 s25, s0, 0x100
	v_mov_b32_e32 v2, 0
	s_addc_u32 s26, s1, 0
	s_mov_b32 s27, -2
	s_waitcnt lgkmcnt(0)
	v_mov_b32_e32 v3, 0
	v_mov_b64_e32 v[4:5], 0
	v_mov_b64_e32 v[6:7], 0
	v_mov_b64_e32 v[8:9], 0
	v_mov_b64_e32 v[18:19], 0
	v_mov_b64_e32 v[20:21], 0
	v_mov_b64_e32 v[22:23], 0
	v_mov_b64_e32 v[24:25], 0
	v_mov_b64_e32 v[34:35], 0
	v_mov_b64_e32 v[36:37], 0
	v_mov_b64_e32 v[38:39], 0
	v_mov_b64_e32 v[40:41], 0
	v_mov_b64_e32 v[50:51], 0
	v_mov_b64_e32 v[52:53], 0
	v_mov_b64_e32 v[54:55], 0
	v_mov_b64_e32 v[56:57], 0
	v_mov_b64_e32 v[10:11], 0
	v_mov_b64_e32 v[12:13], 0
	v_mov_b64_e32 v[14:15], 0
	v_mov_b64_e32 v[16:17], 0
	v_mov_b64_e32 v[26:27], 0
	v_mov_b64_e32 v[28:29], 0
	v_mov_b64_e32 v[30:31], 0
	v_mov_b64_e32 v[32:33], 0
	v_mov_b64_e32 v[42:43], 0
	v_mov_b64_e32 v[44:45], 0
	v_mov_b64_e32 v[46:47], 0
	v_mov_b64_e32 v[48:49], 0
	v_mov_b64_e32 v[58:59], 0
	v_mov_b64_e32 v[60:61], 0
	v_mov_b64_e32 v[62:63], 0
	v_mov_b64_e32 v[64:65], 0
	v_mov_b64_e32 v[66:67], 0
	v_mov_b64_e32 v[68:69], 0
	v_mov_b64_e32 v[70:71], 0
	v_mov_b64_e32 v[72:73], 0
	v_mov_b64_e32 v[82:83], 0
	v_mov_b64_e32 v[84:85], 0
	v_mov_b64_e32 v[86:87], 0
	v_mov_b64_e32 v[88:89], 0
	v_mov_b64_e32 v[98:99], 0
	v_mov_b64_e32 v[100:101], 0
	v_mov_b64_e32 v[102:103], 0
	v_mov_b64_e32 v[104:105], 0
	v_mov_b64_e32 v[138:139], 0
	v_mov_b64_e32 v[140:141], 0
	v_mov_b64_e32 v[142:143], 0
	v_mov_b64_e32 v[144:145], 0
	v_mov_b64_e32 v[74:75], 0
	v_mov_b64_e32 v[76:77], 0
	v_mov_b64_e32 v[78:79], 0
	v_mov_b64_e32 v[80:81], 0
	v_mov_b64_e32 v[90:91], 0
	v_mov_b64_e32 v[92:93], 0
	v_mov_b64_e32 v[94:95], 0
	v_mov_b64_e32 v[96:97], 0
	v_mov_b64_e32 v[106:107], 0
	v_mov_b64_e32 v[108:109], 0
	v_mov_b64_e32 v[110:111], 0
	v_mov_b64_e32 v[112:113], 0
	v_mov_b64_e32 v[146:147], 0
	v_mov_b64_e32 v[148:149], 0
	v_mov_b64_e32 v[150:151], 0
	v_mov_b64_e32 v[152:153], 0
	s_mov_b64 s[60:61], 0x80
	s_waitcnt vmcnt(0)

.LBB0_697:
	s_ashr_i32 s45, s44, 31
	s_lshl_b64 s[4:5], s[44:45], 19
	v_readlane_b32 s24, v254, 43
	v_readlane_b32 s25, v254, 44
	s_add_u32 s4, s24, s4
	s_addc_u32 s5, s25, s5
	s_and_b64 s[24:25], s[40:41], exec
	s_cselect_b32 s24, s5, s7
	s_cselect_b32 s25, s4, s6
	s_ashr_i32 s39, s38, 31
	s_lshl_b64 s[28:29], s[38:39], 19
	s_add_u32 s48, s11, s28
	s_addc_u32 s49, s12, s29
	s_and_b64 s[28:29], s[40:41], exec
	s_cselect_b32 s28, s49, s1
	s_cselect_b32 s29, s48, s0
	s_add_u32 s56, s6, 0x40080
	s_addc_u32 s57, s7, 0
	s_add_u32 s34, s0, 0x100
	v_mov_b32_e32 v2, 0
	s_addc_u32 s35, s1, 0
	s_mov_b32 s39, -2
	v_mov_b32_e32 v3, 0
	v_mov_b64_e32 v[4:5], 0
	v_mov_b64_e32 v[6:7], 0
	v_mov_b64_e32 v[8:9], 0
	v_mov_b64_e32 v[18:19], 0
	v_mov_b64_e32 v[20:21], 0
	v_mov_b64_e32 v[22:23], 0
	v_mov_b64_e32 v[24:25], 0
	v_mov_b64_e32 v[34:35], 0
	v_mov_b64_e32 v[36:37], 0
	v_mov_b64_e32 v[38:39], 0
	v_mov_b64_e32 v[40:41], 0
	v_mov_b64_e32 v[50:51], 0
	v_mov_b64_e32 v[52:53], 0
	v_mov_b64_e32 v[54:55], 0
	v_mov_b64_e32 v[56:57], 0
	v_mov_b64_e32 v[10:11], 0
	v_mov_b64_e32 v[12:13], 0
	v_mov_b64_e32 v[14:15], 0
	v_mov_b64_e32 v[16:17], 0
	v_mov_b64_e32 v[26:27], 0
	v_mov_b64_e32 v[28:29], 0
	v_mov_b64_e32 v[30:31], 0
	v_mov_b64_e32 v[32:33], 0
	v_mov_b64_e32 v[42:43], 0
	v_mov_b64_e32 v[44:45], 0
	v_mov_b64_e32 v[46:47], 0
	v_mov_b64_e32 v[48:49], 0
	v_mov_b64_e32 v[58:59], 0
	v_mov_b64_e32 v[60:61], 0
	v_mov_b64_e32 v[62:63], 0
	v_mov_b64_e32 v[64:65], 0
	v_mov_b64_e32 v[66:67], 0
	v_mov_b64_e32 v[68:69], 0
	v_mov_b64_e32 v[70:71], 0
	v_mov_b64_e32 v[72:73], 0
	v_mov_b64_e32 v[82:83], 0
	v_mov_b64_e32 v[84:85], 0
	v_mov_b64_e32 v[86:87], 0
	v_mov_b64_e32 v[88:89], 0
	v_mov_b64_e32 v[98:99], 0
	v_mov_b64_e32 v[100:101], 0
	v_mov_b64_e32 v[102:103], 0
	v_mov_b64_e32 v[104:105], 0
	s_waitcnt vmcnt(0)
	v_mov_b64_e32 v[114:115], 0
	v_mov_b64_e32 v[116:117], 0
	v_mov_b64_e32 v[118:119], 0
	v_mov_b64_e32 v[120:121], 0
	v_mov_b64_e32 v[74:75], 0
	v_mov_b64_e32 v[76:77], 0
	v_mov_b64_e32 v[78:79], 0
	v_mov_b64_e32 v[80:81], 0
	v_mov_b64_e32 v[90:91], 0
	v_mov_b64_e32 v[92:93], 0
	v_mov_b64_e32 v[94:95], 0
	v_mov_b64_e32 v[96:97], 0
	v_mov_b64_e32 v[106:107], 0
	v_mov_b64_e32 v[108:109], 0
	v_mov_b64_e32 v[110:111], 0
	v_mov_b64_e32 v[112:113], 0
	v_mov_b64_e32 v[122:123], 0
	v_mov_b64_e32 v[124:125], 0
	v_mov_b64_e32 v[126:127], 0
	v_mov_b64_e32 v[128:129], 0
	s_mov_b64 s[60:61], 0x80

.LBB0_777:
	s_ashr_i32 s45, s44, 31
	s_lshl_b64 s[4:5], s[44:45], 19
	s_add_u32 s4, s10, s4
	s_addc_u32 s5, s11, s5
	s_and_b64 s[24:25], s[40:41], exec
	s_cselect_b32 s23, s5, s7
	s_cselect_b32 s24, s4, s6
	s_ashr_i32 s39, s38, 31
	s_lshl_b64 s[28:29], s[38:39], 19
	v_readlane_b32 s34, v254, 43
	v_readlane_b32 s35, v254, 44
	s_add_u32 s48, s34, s28
	s_addc_u32 s49, s35, s29
	s_and_b64 s[28:29], s[40:41], exec
	s_cselect_b32 s25, s49, s1
	s_cselect_b32 s28, s48, s0
	s_add_u32 s42, s6, 0x40080
	s_addc_u32 s43, s7, 0
	s_add_u32 s29, s0, 0x100
	v_mov_b32_e32 v2, 0
	s_addc_u32 s34, s1, 0
	s_mov_b32 s35, -2
	v_mov_b32_e32 v3, 0
	v_mov_b64_e32 v[4:5], 0
	v_mov_b64_e32 v[6:7], 0
	v_mov_b64_e32 v[8:9], 0
	v_mov_b64_e32 v[14:15], 0
	v_mov_b64_e32 v[16:17], 0
	v_mov_b64_e32 v[22:23], 0
	v_mov_b64_e32 v[24:25], 0
	v_mov_b64_e32 v[30:31], 0
	v_mov_b64_e32 v[32:33], 0
	v_mov_b64_e32 v[38:39], 0
	v_mov_b64_e32 v[40:41], 0
	v_mov_b64_e32 v[46:47], 0
	v_mov_b64_e32 v[48:49], 0
	v_mov_b64_e32 v[54:55], 0
	v_mov_b64_e32 v[56:57], 0
	v_mov_b64_e32 v[10:11], 0
	v_mov_b64_e32 v[12:13], 0
	v_mov_b64_e32 v[18:19], 0
	v_mov_b64_e32 v[20:21], 0
	v_mov_b64_e32 v[26:27], 0
	v_mov_b64_e32 v[28:29], 0
	v_mov_b64_e32 v[34:35], 0
	v_mov_b64_e32 v[36:37], 0
	v_mov_b64_e32 v[42:43], 0
	v_mov_b64_e32 v[44:45], 0
	v_mov_b64_e32 v[50:51], 0
	v_mov_b64_e32 v[52:53], 0
	v_mov_b64_e32 v[58:59], 0
	v_mov_b64_e32 v[60:61], 0
	v_mov_b64_e32 v[62:63], 0
	v_mov_b64_e32 v[64:65], 0
	v_mov_b64_e32 v[66:67], 0
	v_mov_b64_e32 v[68:69], 0
	v_mov_b64_e32 v[70:71], 0
	v_mov_b64_e32 v[72:73], 0
	v_mov_b64_e32 v[78:79], 0
	v_mov_b64_e32 v[80:81], 0
	v_mov_b64_e32 v[86:87], 0
	v_mov_b64_e32 v[88:89], 0
	v_mov_b64_e32 v[94:95], 0
	v_mov_b64_e32 v[96:97], 0
	v_mov_b64_e32 v[102:103], 0
	v_mov_b64_e32 v[104:105], 0
	v_mov_b64_e32 v[110:111], 0
	v_mov_b64_e32 v[112:113], 0
	v_mov_b64_e32 v[118:119], 0
	v_mov_b64_e32 v[120:121], 0
	v_mov_b64_e32 v[74:75], 0
	v_mov_b64_e32 v[76:77], 0
	v_mov_b64_e32 v[82:83], 0
	v_mov_b64_e32 v[84:85], 0
	v_mov_b64_e32 v[90:91], 0
	v_mov_b64_e32 v[92:93], 0
	v_mov_b64_e32 v[98:99], 0
	v_mov_b64_e32 v[100:101], 0
	v_mov_b64_e32 v[106:107], 0
	v_mov_b64_e32 v[108:109], 0
	v_mov_b64_e32 v[114:115], 0
	v_mov_b64_e32 v[116:117], 0
	v_mov_b64_e32 v[122:123], 0
	v_mov_b64_e32 v[124:125], 0
	v_mov_b64_e32 v[126:127], 0
	v_mov_b64_e32 v[128:129], 0
	s_mov_b64 s[56:57], 0x80
